# P9 tail round K-split four ways (6/6/5/5 K iterations per workgroup, two row-half owners + two senders) instead of two ways
# baseline (speedup 1.0000x reference)
;     __device__ __forceinline__ const char* Ap(int part) const { return (const char*)A0 + (long)(part == 1) * ((const char*)A1 - (const char*)A0) + (long)(part == 2) * ((const char*)A2 - (const char*)A0); }
;     __device__ __forceinline__ const char* Bp(int part) const { return (const char*)B0 + (long)(part == 1) * ((const char*)B1 - (const char*)B0) + (long)(part == 2) * ((const char*)B2 - (const char*)B0); }
; #define PG8_WAIT_V(n) asm volatile("s_waitcnt vmcnt(" #n ")" ::: "memory")
; template <class Epi, bool GS = false>
; __device__ __forceinline__ void gemm_phase(LAS unsigned char* lds, const Gemm g, const StaticOrder& S, const Epi& E, const int tid) {
;     const int wid = __builtin_amdgcn_readfirstlane(tid >> 6), lane = tid & 63, wr = wid >> 2, wc = wid & 3, fr = lane & 15, fq = lane >> 4;
;     unsigned voffA[2], voffB[2];
; #pragma unroll
;     for (int i = 0; i < 2; ++i) { int R, C; stage_rc(tid * 16 + i * 8192, R, C); const int Rb = Epi::PERM ? ((R & ~31) + perm32(R & 31)) : R;
;         voffA[i] = (unsigned)(R * g.lda + C) * 2u; voffB[i] = (unsigned)(Rb * g.ldb + C) * 2u; }
;     const size_t kstep = (size_t)(BK * 2);
;     const size_t hstepA = (size_t)HALF * g.lda * 2, hstepB = (size_t)HALF * g.ldb * 2;
;     const size_t tstepA = 2 * hstepA, tstepB = 2 * hstepB;
;     const unsigned ldsw = (unsigned)wid * 1024u;
;     const int aoff = lds_byte(wr * 64 + fr, fq * 8), boff = lds_byte(wc * 32 + fr, fq * 8);
;     ...
;     Unit cur, nxt; int ui = 0;
;     if (!S.next(0, cur)) return;
;     f32x4 acc[2][2][4][2];
; #pragma unroll
;     for (int a = 0; a < 2; ++a)
; #pragma unroll
;         for (int b = 0; b < 2; ++b)
; #pragma unroll
;             for (int m = 0; m < 4; ++m)
; #pragma unroll
;                 for (int n = 0; n < 2; ++n) acc[a][b][m][n] = (f32x4){0.f, 0.f, 0.f, 0.f};
;     bf16x8 At[4][2], B0[2][2], B1[2][2];
;     const char* cA = g.Ap(cur.part) + (size_t)cur.pm * tstepA; const char* cB = g.Bp(cur.part) + (size_t)cur.pn * tstepB;
;     PG8_STAGE(PG8_SB(0, 0), cB, voffB); PG8_STAGE(PG8_SB(0, 1), cB + hstepB, voffB); PG8_STAGE(PG8_SA(0, 0), cA, voffA); PG8_STAGE(PG8_SA(0, 1), cA + hstepA, voffA);
;     if (wr == 1) PG8_BAR;
;     PG8_WAIT_V(2); PG8_BAR;
;     PG8_STAGE(PG8_SB(1, 0), cB + kstep, voffB); PG8_STAGE(PG8_SA(1, 0), cA + kstep, voffA); PG8_STAGE(PG8_SB(1, 1), cB + hstepB + kstep, voffB);
;     PG8_WAIT_V(6); PG8_BAR;
.LBB0_980:
	s_or_b64 exec, exec, s[4:5]
	v_readlane_b32 s2, v254, 2
	v_mov_b32_e32 v13, v166
	v_readlane_b32 s3, v254, 3
	s_waitcnt lgkmcnt(0)
	s_barrier
	s_andn2_b64 vcc, exec, s[2:3]
	v_readfirstlane_b32 s4, v13
	s_cbranch_vccnz .LBB0_1016
	s_mov_b32 s100, 0
	s_mov_b32 s101, 0
	s_mov_b32 s58, 0
	v_lshlrev_b32_e32 v0, 4, v13
	v_add_u32_e32 v2, 0x2000, v0
	v_ashrrev_i32_e32 v3, 31, v2
	v_lshrrev_b32_e32 v3, 22, v3
	v_add_u32_e32 v3, v2, v3
	v_ashrrev_i32_e32 v6, 10, v3
	v_mul_i32_i24_e32 v3, 0x400, v6
	v_sub_u32_e32 v2, v2, v3
	v_lshrrev_b32_e32 v3, 4, v2
	v_bitop3_b32 v2, v3, v2, 32 bitop3:0x6c
	v_ashrrev_i32_e32 v3, 31, v2
	v_lshrrev_b32_e32 v3, 26, v3
	v_add_u32_e32 v3, v2, v3
	v_ashrrev_i32_e32 v7, 6, v3
	v_and_b32_e32 v3, 0xc0, v3
	v_sub_u32_e32 v2, v2, v3
	v_ashrrev_i16_sdwa v2, v196, sext(v2) dst_sel:DWORD dst_unused:UNUSED_PAD src0_sel:DWORD src1_sel:BYTE_0
	v_lshlrev_b32_e32 v4, 3, v6
	v_bfe_i32 v9, v2, 0, 16
	v_bfe_i32 v2, v13, 27, 1
	v_and_b32_e32 v4, 0xfffff0, v4
	v_lshrrev_b32_e32 v2, 22, v2
	v_add_u32_e32 v4, v7, v4
	s_movk_i32 s7, 0xb00
	v_lshlrev_b32_e32 v5, 5, v6
	v_add_u32_e32 v2, v0, v2
	v_mul_lo_u32 v4, v4, s7
	v_and_b32_e32 v8, 32, v5
	v_and_b32_e32 v2, 0xfffffc00, v2
	v_or_b32_e32 v4, v4, v8
	v_sub_u32_e32 v0, v0, v2
	v_add_lshl_u32 v162, v4, v9, 1
	v_lshrrev_b32_e32 v2, 4, v0
	v_ashrrev_i32_e32 v4, 31, v13
	v_bitop3_b32 v2, v2, v0, 32 bitop3:0x6c
	v_lshrrev_b32_e32 v4, 26, v4
	v_ashrrev_i32_e32 v0, 31, v2
	v_add_u32_e32 v4, v13, v4
	v_lshrrev_b32_e32 v0, 26, v0
	v_ashrrev_i32_e32 v10, 6, v4
	v_readlane_b32 s2, v255, 20
	v_add_u32_e32 v3, v2, v0
	v_lshlrev_b32_e32 v4, 3, v10
	s_add_u32 s2, s2, 0x2480000
	v_readlane_b32 s3, v255, 22
	v_ashrrev_i32_e32 v0, 6, v3
	v_and_b32_e32 v4, 0xfffff0, v4
	s_addc_u32 s3, s3, 0
	s_ashr_i32 s5, s4, 6
	v_add_u32_e32 v4, v0, v4
	v_and_b32_e32 v3, 0xc0, v3
	v_readlane_b32 s8, v254, 16
	s_ashr_i32 s6, s4, 8
	s_lshl_b32 s10, s5, 10
	v_mul_lo_u32 v4, v4, s7
	v_lshlrev_b32_e32 v5, 5, v10
	v_sub_u32_e32 v2, v2, v3
	s_mul_i32 s7, s8, 0x160000
	v_and_b32_e32 v11, 32, v5
	v_ashrrev_i16_sdwa v2, v196, sext(v2) dst_sel:DWORD dst_unused:UNUSED_PAD src0_sel:DWORD src1_sel:BYTE_0
	s_add_u32 s22, s2, s7
	s_mul_hi_i32 s7, s8, 0x160000
	v_or_b32_e32 v4, v4, v11
	v_bfe_i32 v12, v2, 0, 16
	s_addc_u32 s23, s3, s7
	s_add_i32 s36, s10, 0
	v_add_lshl_u32 v164, v4, v12, 1
	s_add_i32 m0, s36, 0x10000
	v_mov_b32_e32 v165, v1
	global_load_lds_dwordx4 v164, s[22:23]
	s_add_i32 m0, s36, 0x12000
	s_add_u32 s8, s22, 0xb0000
	global_load_lds_dwordx4 v162, s[22:23]
	s_addc_u32 s9, s23, 0
	s_add_i32 m0, s36, 0x14000
	s_add_i32 s37, s36, 0x2000
	global_load_lds_dwordx4 v164, s[8:9]
	s_add_i32 m0, s36, 0x16000
	s_add_i32 s38, s36, 0x4000
	global_load_lds_dwordx4 v162, s[8:9]
	v_readlane_b32 s8, v254, 19
	s_mov_b32 m0, s36
	v_readlane_b32 s9, v254, 20
	s_add_i32 s39, s36, 0x6000
	v_mov_b32_e32 v163, v1
	s_cmp_eq_u32 s6, 1
	v_lshl_add_u64 v[2:3], s[22:23], 0, v[164:165]
	v_lshl_add_u64 v[4:5], s[22:23], 0, v[162:163]
	global_load_lds_dwordx4 v164, s[8:9]
	s_mov_b32 m0, s37
	s_nop 0
	global_load_lds_dwordx4 v162, s[8:9]
	v_readlane_b32 s8, v254, 21
	s_mov_b32 m0, s38
	v_readlane_b32 s9, v254, 22
	s_nop 4
	global_load_lds_dwordx4 v164, s[8:9]
	s_mov_b32 m0, s39
	s_nop 0
	global_load_lds_dwordx4 v162, s[8:9]
	s_cselect_b64 s[8:9], -1, 0
	s_cmp_lg_u32 s6, 1
	s_cbranch_scc1 .LBB0_983
	s_barrier

;     __device__ __forceinline__ bool next(int i, Unit& u) const {
;         const int r = i / np; u.part = i - r * np;
;         long L = (long)r * G + c;
;         if (L >= split_from) { const long Ls = L - split_from; if (Ls >= 2L * (nwg - split_from)) return false; L = split_from + (Ls >> 1); u.part = 1 + (int)(Ls & 1); }
;         if (L >= nwg) return false;
;         int wgid = (int)L; { const int q = nwg / NXCD, rr = nwg % NXCD, xcd = wgid % NXCD, off = wgid / NXCD; wgid = (xcd < rr ? xcd * (q + 1) : rr * (q + 1) + (xcd - rr) * q) + off; }
;         const int nig = WGM * nN, gid = wgid / nig, fm = gid * WGM, gsz = (nM - fm) < WGM ? (nM - fm) : WGM;
;         u.pm = fm + ((wgid % nig) % gsz); u.pn = (wgid % nig) / gsz; return true;
;     }
.LBB0_986:
	s_add_i32 s45, s45, 1
	v_readlane_b32 s4, v253, 53
	v_readlane_b32 s6, v252, 0
	s_mul_i32 s4, s45, s4
	v_readlane_b32 s7, v252, 1
	s_mul_hi_u32 s5, s45, s6
	s_add_i32 s5, s5, s4
	s_mul_i32 s4, s45, s6
	v_readlane_b32 s6, v254, 38
	v_readlane_b32 s7, v254, 39
	s_add_u32 s4, s4, s6
	s_addc_u32 s5, s5, s7
	s_mov_b32 s101, 0
	s_mov_b32 s58, 0
	s_cmp_lt_u32 s4, 0x200
	s_cbranch_scc1 .Lk4_ns
	s_sub_i32 s16, s4, 0x200
	s_and_b32 s101, s16, 3
	s_mul_i32 s58, s101, 0x600
	s_cmp_eq_u32 s101, 3
	s_cselect_b32 s17, 0x100, 0
	s_sub_u32 s58, s58, s17
	s_add_i32 s17, s101, 1
	s_min_u32 s17, s17, 3
	s_lshl_b32 s101, s101, 2
	s_add_i32 s101, s101, s17
	s_lshr_b32 s17, s16, 2
	s_add_i32 s4, s17, 0x200
	s_cmp_lt_u32 s16, 0x80
	s_cselect_b32 s4, s4, 0x7fff

;     __device__ __forceinline__ const char* Ap(int part) const { return (const char*)A0 + (long)(part == 1) * ((const char*)A1 - (const char*)A0) + (long)(part == 2) * ((const char*)A2 - (const char*)A0); }
;     __device__ __forceinline__ const char* Bp(int part) const { return (const char*)B0 + (long)(part == 1) * ((const char*)B1 - (const char*)B0) + (long)(part == 2) * ((const char*)B2 - (const char*)B0); }
; template <class Epi, bool GS = false>
; __device__ __forceinline__ void gemm_phase(LAS unsigned char* lds, const Gemm g, const StaticOrder& S, const Epi& E, const int tid) {
;     ...
;         const bool has_next = S.next(ui + 1, nxt);
;         const char* nA = has_next ? g.Ap(nxt.part) + (size_t)nxt.pm * tstepA : cA; const char* nB = has_next ? g.Bp(nxt.part) + (size_t)nxt.pn * tstepB : cB;
;         const int nt = g.Kp(cur.part) / BK;
;         const int seg = (GS && cur.part == 0) ? 8 : nt;
;         for (int tg = 0; tg < nt; tg += seg) {
;         for (int t = tg; t < tg + seg; t += 2) {
;             const bool last = (t == nt - 2);
;             const char* a1 = cA + (size_t)(t + 1) * kstep;
;             const char* a2 = last ? nA : cA + (size_t)(t + 2) * kstep; const char* b2 = last ? nB : cB + (size_t)(t + 2) * kstep;
;     ...
; #pragma unroll
;         for (int a = 0; a < 2; ++a)
; #pragma unroll
;             for (int b = 0; b < 2; ++b)
; #pragma unroll
;                 for (int m = 0; m < 4; ++m)
; #pragma unroll
;                     for (int n = 0; n < 2; ++n) acc[a][b][m][n] = (f32x4){0.f, 0.f, 0.f, 0.f};
.LBB0_988:
	s_nop 0
	v_cndmask_b32_e64 v0, 0, 1, s[6:7]
	v_cmp_ne_u32_e64 s[4:5], 1, v0
	s_andn2_b64 vcc, exec, s[6:7]
	s_mov_b64 s[6:7], s[20:21]
	s_cbranch_vccnz .LBB0_990
	s_mul_i32 s6, s47, 0x160000
	s_mul_hi_i32 s7, s47, 0x160000
	s_add_u32 s6, s18, s6
	s_addc_u32 s7, s19, s7
	s_add_u32 s6, s6, s58
	s_addc_u32 s7, s7, 0
.LBB0_990:
	s_and_b64 vcc, exec, s[4:5]
	s_mov_b64 s[16:17], s[22:23]
	s_cbranch_vccnz .LBB0_992
	s_mul_i32 s16, s46, 0x160000
	s_mul_hi_i32 s17, s46, 0x160000
	s_add_u32 s16, s2, s16
	s_addc_u32 s17, s3, s17
	s_add_u32 s16, s16, s58
	s_addc_u32 s17, s17, 0
.LBB0_992:
	s_add_u32 s50, s22, 0x100
	v_mov_b32_e32 v2, 0
	s_addc_u32 s51, s23, 0
	s_mov_b32 s52, -2
	s_cmp_eq_u32 s100, 0
	s_cbranch_scc1 .Lk4_l
	s_cmp_lt_u32 s100, 8
	s_cselect_b32 s52, 30, 32
.Lk4_l:
	v_mov_b32_e32 v3, v2
	v_mov_b32_e32 v4, v2
	v_mov_b32_e32 v5, v2
	v_mov_b32_e32 v6, v2
	v_mov_b32_e32 v7, v2
	v_mov_b32_e32 v8, v2
	v_mov_b32_e32 v9, v2
	v_mov_b32_e32 v18, v2
	v_mov_b32_e32 v19, v2
	v_mov_b32_e32 v20, v2
	v_mov_b32_e32 v21, v2
	v_mov_b32_e32 v22, v2
	v_mov_b32_e32 v23, v2
	v_mov_b32_e32 v24, v2
	v_mov_b32_e32 v25, v2
	v_mov_b32_e32 v34, v2
	v_mov_b32_e32 v35, v2
	v_mov_b32_e32 v36, v2
	v_mov_b32_e32 v37, v2
	v_mov_b32_e32 v38, v2
	v_mov_b32_e32 v39, v2
	v_mov_b32_e32 v40, v2
	v_mov_b32_e32 v41, v2
	v_mov_b32_e32 v50, v2
	v_mov_b32_e32 v51, v2
	v_mov_b32_e32 v52, v2
	v_mov_b32_e32 v53, v2
	v_mov_b32_e32 v54, v2
	v_mov_b32_e32 v55, v2
	v_mov_b32_e32 v56, v2
	v_mov_b32_e32 v57, v2
	v_mov_b32_e32 v10, v2
	v_mov_b32_e32 v11, v2
	v_mov_b32_e32 v12, v2
	v_mov_b32_e32 v13, v2
	v_mov_b32_e32 v14, v2
	v_mov_b32_e32 v15, v2
	v_mov_b32_e32 v16, v2
	v_mov_b32_e32 v17, v2
	v_mov_b32_e32 v26, v2
	v_mov_b32_e32 v27, v2
	v_mov_b32_e32 v28, v2
	v_mov_b32_e32 v29, v2
	v_mov_b32_e32 v30, v2
	v_mov_b32_e32 v31, v2
	v_mov_b32_e32 v32, v2
	v_mov_b32_e32 v33, v2
	v_mov_b32_e32 v42, v2
	v_mov_b32_e32 v43, v2
	v_mov_b32_e32 v44, v2
	v_mov_b32_e32 v45, v2
	v_mov_b32_e32 v46, v2
	v_mov_b32_e32 v47, v2
	v_mov_b32_e32 v48, v2
	v_mov_b32_e32 v49, v2
	v_mov_b32_e32 v58, v2
	v_mov_b32_e32 v59, v2
	v_mov_b32_e32 v60, v2
	v_mov_b32_e32 v61, v2
	v_mov_b32_e32 v62, v2
	v_mov_b32_e32 v63, v2
	v_mov_b32_e32 v64, v2
	v_mov_b32_e32 v65, v2
	v_mov_b32_e32 v66, v2
	v_mov_b32_e32 v67, v2
	v_mov_b32_e32 v68, v2
	v_mov_b32_e32 v69, v2
	v_mov_b32_e32 v70, v2
	v_mov_b32_e32 v71, v2
	v_mov_b32_e32 v72, v2
	v_mov_b32_e32 v73, v2
	v_mov_b32_e32 v82, v2
	v_mov_b32_e32 v83, v2
	v_mov_b32_e32 v84, v2
	v_mov_b32_e32 v85, v2
	v_mov_b32_e32 v86, v2
	v_mov_b32_e32 v87, v2
	v_mov_b32_e32 v88, v2
	v_mov_b32_e32 v89, v2
	v_mov_b32_e32 v98, v2
	v_mov_b32_e32 v99, v2
	v_mov_b32_e32 v100, v2
	v_mov_b32_e32 v101, v2
	v_mov_b32_e32 v102, v2
	v_mov_b32_e32 v103, v2
	v_mov_b32_e32 v104, v2
	v_mov_b32_e32 v105, v2
	v_mov_b32_e32 v114, v2
	v_mov_b32_e32 v115, v2
	v_mov_b32_e32 v116, v2
	v_mov_b32_e32 v117, v2
	v_mov_b32_e32 v118, v2
	v_mov_b32_e32 v119, v2
	v_mov_b32_e32 v120, v2
	v_mov_b32_e32 v121, v2
	v_mov_b32_e32 v74, v2
	v_mov_b32_e32 v75, v2
	v_mov_b32_e32 v76, v2
	v_mov_b32_e32 v77, v2
	v_mov_b32_e32 v78, v2
	v_mov_b32_e32 v79, v2
	v_mov_b32_e32 v80, v2
	v_mov_b32_e32 v81, v2
	v_mov_b32_e32 v90, v2
	v_mov_b32_e32 v91, v2
	v_mov_b32_e32 v92, v2
	v_mov_b32_e32 v93, v2
	v_mov_b32_e32 v94, v2
	v_mov_b32_e32 v95, v2
	v_mov_b32_e32 v96, v2
	v_mov_b32_e32 v97, v2
	v_mov_b32_e32 v106, v2
	v_mov_b32_e32 v107, v2
	v_mov_b32_e32 v108, v2
	v_mov_b32_e32 v109, v2
	v_mov_b32_e32 v110, v2
	v_mov_b32_e32 v111, v2
	v_mov_b32_e32 v112, v2
	v_mov_b32_e32 v113, v2
	v_mov_b32_e32 v122, v2
	v_mov_b32_e32 v123, v2
	v_mov_b32_e32 v124, v2
	v_mov_b32_e32 v125, v2
	v_mov_b32_e32 v126, v2
	v_mov_b32_e32 v127, v2
	v_mov_b32_e32 v128, v2
	v_mov_b32_e32 v129, v2

; #define PG8_BAR __builtin_amdgcn_s_barrier()
; template <class Epi, bool GS = false>
; __device__ __forceinline__ void gemm_phase(LAS unsigned char* lds, const Gemm g, const StaticOrder& S, const Epi& E, const int tid) {
;     ...
;         if (wr == 0) PG8_BAR;
;         E(acc, cur, wr, wc, fr, fq);
.LBB0_996:
	s_cmp_eq_u32 s100, 0
	s_cbranch_scc1 .Lk4_done
	v_readlane_b32 s28, v252, 2
	s_lshr_b32 s28, s28, 9
	s_lshr_b32 s29, s28, 2
	s_and_b32 s28, s28, 3
	s_mul_i32 s30, s29, 0xc0000
	s_add_i32 s31, s30, 0x60000
	v_lshlrev_b32_e32 v130, 4, v166
	s_add_u32 s54, s26, 0x1d780000
	s_addc_u32 s55, s27, 0
	s_lshl_b32 s51, s29, 5
	s_addk_i32 s51, 0x3a00
	s_cmp_eq_u32 s28, 0
	s_cbranch_scc0 .Lk4_s1
	s_add_i32 s53, s31, 0
	v_add_u32_e32 v131, s53, v130
	global_store_dwordx4 v131, v[2:5], s[12:13] sc0 sc1
	v_add_u32_e32 v131, 0x2000, v131
	global_store_dwordx4 v131, v[6:9], s[12:13] sc0 sc1
	v_add_u32_e32 v131, 0x2000, v131
	global_store_dwordx4 v131, v[10:13], s[12:13] sc0 sc1
	v_add_u32_e32 v131, 0x2000, v131
	global_store_dwordx4 v131, v[14:17], s[12:13] sc0 sc1
	v_add_u32_e32 v131, 0x2000, v131
	global_store_dwordx4 v131, v[18:21], s[12:13] sc0 sc1
	v_add_u32_e32 v131, 0x2000, v131
	global_store_dwordx4 v131, v[22:25], s[12:13] sc0 sc1
	v_add_u32_e32 v131, 0x2000, v131
	global_store_dwordx4 v131, v[26:29], s[12:13] sc0 sc1
	v_add_u32_e32 v131, 0x2000, v131
	global_store_dwordx4 v131, v[30:33], s[12:13] sc0 sc1
	v_add_u32_e32 v131, 0x2000, v131
	global_store_dwordx4 v131, v[34:37], s[12:13] sc0 sc1
	v_add_u32_e32 v131, 0x2000, v131
	global_store_dwordx4 v131, v[38:41], s[12:13] sc0 sc1
	v_add_u32_e32 v131, 0x2000, v131
	global_store_dwordx4 v131, v[42:45], s[12:13] sc0 sc1
	v_add_u32_e32 v131, 0x2000, v131
	global_store_dwordx4 v131, v[46:49], s[12:13] sc0 sc1
	v_add_u32_e32 v131, 0x2000, v131
	global_store_dwordx4 v131, v[50:53], s[12:13] sc0 sc1
	v_add_u32_e32 v131, 0x2000, v131
	global_store_dwordx4 v131, v[54:57], s[12:13] sc0 sc1
	v_add_u32_e32 v131, 0x2000, v131
	global_store_dwordx4 v131, v[58:61], s[12:13] sc0 sc1
	v_add_u32_e32 v131, 0x2000, v131
	global_store_dwordx4 v131, v[62:65], s[12:13] sc0 sc1
	v_add_u32_e32 v131, 0x2000, v131
	s_branch .Lk4_sent
.Lk4_s1:
	s_cmp_eq_u32 s28, 1
	s_cbranch_scc0 .Lk4_s2
	s_add_i32 s53, s30, 0
	v_add_u32_e32 v131, s53, v130
	global_store_dwordx4 v131, v[66:69], s[12:13] sc0 sc1
	v_add_u32_e32 v131, 0x2000, v131
	global_store_dwordx4 v131, v[70:73], s[12:13] sc0 sc1
	v_add_u32_e32 v131, 0x2000, v131
	global_store_dwordx4 v131, v[74:77], s[12:13] sc0 sc1
	v_add_u32_e32 v131, 0x2000, v131
	global_store_dwordx4 v131, v[78:81], s[12:13] sc0 sc1
	v_add_u32_e32 v131, 0x2000, v131
	global_store_dwordx4 v131, v[82:85], s[12:13] sc0 sc1
	v_add_u32_e32 v131, 0x2000, v131
	global_store_dwordx4 v131, v[86:89], s[12:13] sc0 sc1
	v_add_u32_e32 v131, 0x2000, v131
	global_store_dwordx4 v131, v[90:93], s[12:13] sc0 sc1
	v_add_u32_e32 v131, 0x2000, v131
	global_store_dwordx4 v131, v[94:97], s[12:13] sc0 sc1
	v_add_u32_e32 v131, 0x2000, v131
	global_store_dwordx4 v131, v[98:101], s[12:13] sc0 sc1
	v_add_u32_e32 v131, 0x2000, v131
	global_store_dwordx4 v131, v[102:105], s[12:13] sc0 sc1
	v_add_u32_e32 v131, 0x2000, v131
	global_store_dwordx4 v131, v[106:109], s[12:13] sc0 sc1
	v_add_u32_e32 v131, 0x2000, v131
	global_store_dwordx4 v131, v[110:113], s[12:13] sc0 sc1
	v_add_u32_e32 v131, 0x2000, v131
	global_store_dwordx4 v131, v[114:117], s[12:13] sc0 sc1
	v_add_u32_e32 v131, 0x2000, v131
	global_store_dwordx4 v131, v[118:121], s[12:13] sc0 sc1
	v_add_u32_e32 v131, 0x2000, v131
	global_store_dwordx4 v131, v[122:125], s[12:13] sc0 sc1
	v_add_u32_e32 v131, 0x2000, v131
	global_store_dwordx4 v131, v[126:129], s[12:13] sc0 sc1
	v_add_u32_e32 v131, 0x2000, v131
	s_branch .Lk4_sent
.Lk4_s2:
	s_add_i32 s50, s28, -1
	s_lshl_b32 s50, s50, 17
	s_add_i32 s53, s30, s50
	v_add_u32_e32 v131, s53, v130
	global_store_dwordx4 v131, v[66:69], s[12:13] sc0 sc1
	v_add_u32_e32 v131, 0x2000, v131
	global_store_dwordx4 v131, v[70:73], s[12:13] sc0 sc1
	v_add_u32_e32 v131, 0x2000, v131
	global_store_dwordx4 v131, v[74:77], s[12:13] sc0 sc1
	v_add_u32_e32 v131, 0x2000, v131
	global_store_dwordx4 v131, v[78:81], s[12:13] sc0 sc1
	v_add_u32_e32 v131, 0x2000, v131
	global_store_dwordx4 v131, v[82:85], s[12:13] sc0 sc1
	v_add_u32_e32 v131, 0x2000, v131
	global_store_dwordx4 v131, v[86:89], s[12:13] sc0 sc1
	v_add_u32_e32 v131, 0x2000, v131
	global_store_dwordx4 v131, v[90:93], s[12:13] sc0 sc1
	v_add_u32_e32 v131, 0x2000, v131
	global_store_dwordx4 v131, v[94:97], s[12:13] sc0 sc1
	v_add_u32_e32 v131, 0x2000, v131
	global_store_dwordx4 v131, v[98:101], s[12:13] sc0 sc1
	v_add_u32_e32 v131, 0x2000, v131
	global_store_dwordx4 v131, v[102:105], s[12:13] sc0 sc1
	v_add_u32_e32 v131, 0x2000, v131
	global_store_dwordx4 v131, v[106:109], s[12:13] sc0 sc1
	v_add_u32_e32 v131, 0x2000, v131
	global_store_dwordx4 v131, v[110:113], s[12:13] sc0 sc1
	v_add_u32_e32 v131, 0x2000, v131
	global_store_dwordx4 v131, v[114:117], s[12:13] sc0 sc1
	v_add_u32_e32 v131, 0x2000, v131
	global_store_dwordx4 v131, v[118:121], s[12:13] sc0 sc1
	v_add_u32_e32 v131, 0x2000, v131
	global_store_dwordx4 v131, v[122:125], s[12:13] sc0 sc1
	v_add_u32_e32 v131, 0x2000, v131
	global_store_dwordx4 v131, v[126:129], s[12:13] sc0 sc1
	v_add_u32_e32 v131, 0x2000, v131
	s_add_i32 s53, s31, s50
	v_add_u32_e32 v131, s53, v130
	global_store_dwordx4 v131, v[2:5], s[12:13] sc0 sc1
	v_add_u32_e32 v131, 0x2000, v131
	global_store_dwordx4 v131, v[6:9], s[12:13] sc0 sc1
	v_add_u32_e32 v131, 0x2000, v131
	global_store_dwordx4 v131, v[10:13], s[12:13] sc0 sc1
	v_add_u32_e32 v131, 0x2000, v131
	global_store_dwordx4 v131, v[14:17], s[12:13] sc0 sc1
	v_add_u32_e32 v131, 0x2000, v131
	global_store_dwordx4 v131, v[18:21], s[12:13] sc0 sc1
	v_add_u32_e32 v131, 0x2000, v131
	global_store_dwordx4 v131, v[22:25], s[12:13] sc0 sc1
	v_add_u32_e32 v131, 0x2000, v131
	global_store_dwordx4 v131, v[26:29], s[12:13] sc0 sc1
	v_add_u32_e32 v131, 0x2000, v131
	global_store_dwordx4 v131, v[30:33], s[12:13] sc0 sc1
	v_add_u32_e32 v131, 0x2000, v131
	global_store_dwordx4 v131, v[34:37], s[12:13] sc0 sc1
	v_add_u32_e32 v131, 0x2000, v131
	global_store_dwordx4 v131, v[38:41], s[12:13] sc0 sc1
	v_add_u32_e32 v131, 0x2000, v131
	global_store_dwordx4 v131, v[42:45], s[12:13] sc0 sc1
	v_add_u32_e32 v131, 0x2000, v131
	global_store_dwordx4 v131, v[46:49], s[12:13] sc0 sc1
	v_add_u32_e32 v131, 0x2000, v131
	global_store_dwordx4 v131, v[50:53], s[12:13] sc0 sc1
	v_add_u32_e32 v131, 0x2000, v131
	global_store_dwordx4 v131, v[54:57], s[12:13] sc0 sc1
	v_add_u32_e32 v131, 0x2000, v131
	global_store_dwordx4 v131, v[58:61], s[12:13] sc0 sc1
	v_add_u32_e32 v131, 0x2000, v131
	global_store_dwordx4 v131, v[62:65], s[12:13] sc0 sc1
	v_add_u32_e32 v131, 0x2000, v131
; #define PG8_BAR __builtin_amdgcn_s_barrier()
; template <class Epi, bool GS = false>
; __device__ __forceinline__ void gemm_phase(LAS unsigned char* lds, const Gemm g, const StaticOrder& S, const Epi& E, const int tid) {
;     ...
;         if (wr == 0) PG8_BAR;
;         E(acc, cur, wr, wc, fr, fq);
.Lk4_sent:
	s_waitcnt vmcnt(0)
	s_barrier
	v_readfirstlane_b32 s50, v166
	s_nop 0
	s_cmp_lt_u32 s50, 64
	s_cbranch_scc0 .Lk4_wait
	v_mov_b32_e32 v133, 1
	s_cmp_eq_u32 s28, 0
	s_cbranch_scc0 .Lk4_f1
	s_add_i32 s53, s51, 16
	v_mov_b32_e32 v132, s53
	global_store_dword v132, v133, s[54:55] sc0 sc1
	s_branch .Lk4_poll0
.Lk4_f1:
	s_cmp_eq_u32 s28, 1
	s_cbranch_scc0 .Lk4_f2
	v_mov_b32_e32 v132, s51
	global_store_dword v132, v133, s[54:55] sc0 sc1
	s_branch .Lk4_poll0
.Lk4_f2:
	s_add_i32 s50, s28, -1
	s_lshl_b32 s50, s50, 2
	s_add_i32 s53, s51, s50
	v_mov_b32_e32 v132, s53
	global_store_dword v132, v133, s[54:55] sc0 sc1
	s_add_i32 s53, s53, 16
	v_mov_b32_e32 v132, s53
	global_store_dword v132, v133, s[54:55] sc0 sc1
	s_waitcnt vmcnt(0)
	s_branch .Lk4_wait
.Lk4_poll0:
	s_lshl_b32 s50, s28, 4
	s_add_i32 s53, s51, s50
	v_mov_b32_e32 v134, s53
	s_mov_b32 s53, 0
.Lk4_poll:
	global_load_dwordx3 v[136:138], v134, s[54:55] sc0 sc1
	s_waitcnt vmcnt(0)
	v_and_b32_e32 v136, v136, v137
	v_and_b32_e32 v136, v136, v138
	s_nop 0
	v_readfirstlane_b32 s52, v136
	s_add_i32 s53, s53, 1
	s_cmp_eq_u32 s52, 1
	s_cbranch_scc1 .Lk4_got
	s_sleep 1
	s_cmp_lt_u32 s53, 0x8000
	s_cbranch_scc1 .Lk4_poll
.Lk4_got:
	v_mov_b32_e32 v136, 0
	v_mov_b32_e32 v137, 0
	v_mov_b32_e32 v138, 0
	global_store_dwordx3 v134, v[136:138], s[54:55] sc0 sc1
	s_waitcnt vmcnt(0)
.Lk4_wait:
	s_barrier
	s_cmp_gt_u32 s28, 1
	s_cbranch_scc1 .Lk4_done
	s_cmp_eq_u32 s28, 0
	s_cbranch_scc0 .Lk4_r1
	s_add_i32 s53, s30, 0x0
	v_add_u32_e32 v131, s53, v130
	global_load_dwordx4 v[2:5], v131, s[12:13] sc0 sc1
	v_add_u32_e32 v131, 0x2000, v131
	global_load_dwordx4 v[6:9], v131, s[12:13] sc0 sc1
	v_add_u32_e32 v131, 0x2000, v131
	global_load_dwordx4 v[10:13], v131, s[12:13] sc0 sc1
	v_add_u32_e32 v131, 0x2000, v131
	global_load_dwordx4 v[14:17], v131, s[12:13] sc0 sc1
	v_add_u32_e32 v131, 0x2000, v131
	global_load_dwordx4 v[18:21], v131, s[12:13] sc0 sc1
	v_add_u32_e32 v131, 0x2000, v131
	global_load_dwordx4 v[22:25], v131, s[12:13] sc0 sc1
	v_add_u32_e32 v131, 0x2000, v131
	global_load_dwordx4 v[26:29], v131, s[12:13] sc0 sc1
	v_add_u32_e32 v131, 0x2000, v131
	global_load_dwordx4 v[30:33], v131, s[12:13] sc0 sc1
	v_add_u32_e32 v131, 0x2000, v131
	global_load_dwordx4 v[34:37], v131, s[12:13] sc0 sc1
	v_add_u32_e32 v131, 0x2000, v131
	global_load_dwordx4 v[38:41], v131, s[12:13] sc0 sc1
	v_add_u32_e32 v131, 0x2000, v131
	global_load_dwordx4 v[42:45], v131, s[12:13] sc0 sc1
	v_add_u32_e32 v131, 0x2000, v131
	global_load_dwordx4 v[46:49], v131, s[12:13] sc0 sc1
	v_add_u32_e32 v131, 0x2000, v131
	global_load_dwordx4 v[50:53], v131, s[12:13] sc0 sc1
	v_add_u32_e32 v131, 0x2000, v131
	global_load_dwordx4 v[54:57], v131, s[12:13] sc0 sc1
	v_add_u32_e32 v131, 0x2000, v131
	global_load_dwordx4 v[58:61], v131, s[12:13] sc0 sc1
	v_add_u32_e32 v131, 0x2000, v131
	global_load_dwordx4 v[62:65], v131, s[12:13] sc0 sc1
	v_add_u32_e32 v131, 0x2000, v131
	s_waitcnt vmcnt(15)
	v_pk_add_f32 v[66:67], v[66:67], v[2:3]
	v_pk_add_f32 v[68:69], v[68:69], v[4:5]
	s_waitcnt vmcnt(14)
	v_pk_add_f32 v[70:71], v[70:71], v[6:7]
	v_pk_add_f32 v[72:73], v[72:73], v[8:9]
	s_waitcnt vmcnt(13)
	v_pk_add_f32 v[74:75], v[74:75], v[10:11]
	v_pk_add_f32 v[76:77], v[76:77], v[12:13]
	s_waitcnt vmcnt(12)
	v_pk_add_f32 v[78:79], v[78:79], v[14:15]
	v_pk_add_f32 v[80:81], v[80:81], v[16:17]
	s_waitcnt vmcnt(11)
	v_pk_add_f32 v[82:83], v[82:83], v[18:19]
	v_pk_add_f32 v[84:85], v[84:85], v[20:21]
	s_waitcnt vmcnt(10)
	v_pk_add_f32 v[86:87], v[86:87], v[22:23]
	v_pk_add_f32 v[88:89], v[88:89], v[24:25]
	s_waitcnt vmcnt(9)
	v_pk_add_f32 v[90:91], v[90:91], v[26:27]
	v_pk_add_f32 v[92:93], v[92:93], v[28:29]
	s_waitcnt vmcnt(8)
	v_pk_add_f32 v[94:95], v[94:95], v[30:31]
	v_pk_add_f32 v[96:97], v[96:97], v[32:33]
	s_waitcnt vmcnt(7)
	v_pk_add_f32 v[98:99], v[98:99], v[34:35]
	v_pk_add_f32 v[100:101], v[100:101], v[36:37]
	s_waitcnt vmcnt(6)
	v_pk_add_f32 v[102:103], v[102:103], v[38:39]
	v_pk_add_f32 v[104:105], v[104:105], v[40:41]
	s_waitcnt vmcnt(5)
	v_pk_add_f32 v[106:107], v[106:107], v[42:43]
	v_pk_add_f32 v[108:109], v[108:109], v[44:45]
	s_waitcnt vmcnt(4)
	v_pk_add_f32 v[110:111], v[110:111], v[46:47]
	v_pk_add_f32 v[112:113], v[112:113], v[48:49]
	s_waitcnt vmcnt(3)
	v_pk_add_f32 v[114:115], v[114:115], v[50:51]
	v_pk_add_f32 v[116:117], v[116:117], v[52:53]
	s_waitcnt vmcnt(2)
	v_pk_add_f32 v[118:119], v[118:119], v[54:55]
	v_pk_add_f32 v[120:121], v[120:121], v[56:57]
	s_waitcnt vmcnt(1)
	v_pk_add_f32 v[122:123], v[122:123], v[58:59]
	v_pk_add_f32 v[124:125], v[124:125], v[60:61]
	s_waitcnt vmcnt(0)
	v_pk_add_f32 v[126:127], v[126:127], v[62:63]
	v_pk_add_f32 v[128:129], v[128:129], v[64:65]
	s_nop 1
	s_add_i32 s53, s30, 0x20000
	v_add_u32_e32 v131, s53, v130
	global_load_dwordx4 v[2:5], v131, s[12:13] sc0 sc1
	v_add_u32_e32 v131, 0x2000, v131
	global_load_dwordx4 v[6:9], v131, s[12:13] sc0 sc1
	v_add_u32_e32 v131, 0x2000, v131
	global_load_dwordx4 v[10:13], v131, s[12:13] sc0 sc1
	v_add_u32_e32 v131, 0x2000, v131
	global_load_dwordx4 v[14:17], v131, s[12:13] sc0 sc1
	v_add_u32_e32 v131, 0x2000, v131
	global_load_dwordx4 v[18:21], v131, s[12:13] sc0 sc1
	v_add_u32_e32 v131, 0x2000, v131
	global_load_dwordx4 v[22:25], v131, s[12:13] sc0 sc1
	v_add_u32_e32 v131, 0x2000, v131
	global_load_dwordx4 v[26:29], v131, s[12:13] sc0 sc1
	v_add_u32_e32 v131, 0x2000, v131
	global_load_dwordx4 v[30:33], v131, s[12:13] sc0 sc1
	v_add_u32_e32 v131, 0x2000, v131
	global_load_dwordx4 v[34:37], v131, s[12:13] sc0 sc1
	v_add_u32_e32 v131, 0x2000, v131
	global_load_dwordx4 v[38:41], v131, s[12:13] sc0 sc1
	v_add_u32_e32 v131, 0x2000, v131
	global_load_dwordx4 v[42:45], v131, s[12:13] sc0 sc1
	v_add_u32_e32 v131, 0x2000, v131
	global_load_dwordx4 v[46:49], v131, s[12:13] sc0 sc1
	v_add_u32_e32 v131, 0x2000, v131
	global_load_dwordx4 v[50:53], v131, s[12:13] sc0 sc1
	v_add_u32_e32 v131, 0x2000, v131
	global_load_dwordx4 v[54:57], v131, s[12:13] sc0 sc1
	v_add_u32_e32 v131, 0x2000, v131
	global_load_dwordx4 v[58:61], v131, s[12:13] sc0 sc1
	v_add_u32_e32 v131, 0x2000, v131
	global_load_dwordx4 v[62:65], v131, s[12:13] sc0 sc1
	v_add_u32_e32 v131, 0x2000, v131
	s_waitcnt vmcnt(15)
; #define PG8_BAR __builtin_amdgcn_s_barrier()
; template <class Epi, bool GS = false>
; __device__ __forceinline__ void gemm_phase(LAS unsigned char* lds, const Gemm g, const StaticOrder& S, const Epi& E, const int tid) {
;     ...
;         if (wr == 0) PG8_BAR;
;         E(acc, cur, wr, wc, fr, fq);
	v_pk_add_f32 v[66:67], v[66:67], v[2:3]
	v_pk_add_f32 v[68:69], v[68:69], v[4:5]
	s_waitcnt vmcnt(14)
	v_pk_add_f32 v[70:71], v[70:71], v[6:7]
	v_pk_add_f32 v[72:73], v[72:73], v[8:9]
	s_waitcnt vmcnt(13)
	v_pk_add_f32 v[74:75], v[74:75], v[10:11]
	v_pk_add_f32 v[76:77], v[76:77], v[12:13]
	s_waitcnt vmcnt(12)
	v_pk_add_f32 v[78:79], v[78:79], v[14:15]
	v_pk_add_f32 v[80:81], v[80:81], v[16:17]
	s_waitcnt vmcnt(11)
	v_pk_add_f32 v[82:83], v[82:83], v[18:19]
	v_pk_add_f32 v[84:85], v[84:85], v[20:21]
	s_waitcnt vmcnt(10)
	v_pk_add_f32 v[86:87], v[86:87], v[22:23]
	v_pk_add_f32 v[88:89], v[88:89], v[24:25]
	s_waitcnt vmcnt(9)
	v_pk_add_f32 v[90:91], v[90:91], v[26:27]
	v_pk_add_f32 v[92:93], v[92:93], v[28:29]
	s_waitcnt vmcnt(8)
	v_pk_add_f32 v[94:95], v[94:95], v[30:31]
	v_pk_add_f32 v[96:97], v[96:97], v[32:33]
	s_waitcnt vmcnt(7)
	v_pk_add_f32 v[98:99], v[98:99], v[34:35]
	v_pk_add_f32 v[100:101], v[100:101], v[36:37]
	s_waitcnt vmcnt(6)
	v_pk_add_f32 v[102:103], v[102:103], v[38:39]
	v_pk_add_f32 v[104:105], v[104:105], v[40:41]
	s_waitcnt vmcnt(5)
	v_pk_add_f32 v[106:107], v[106:107], v[42:43]
	v_pk_add_f32 v[108:109], v[108:109], v[44:45]
	s_waitcnt vmcnt(4)
	v_pk_add_f32 v[110:111], v[110:111], v[46:47]
	v_pk_add_f32 v[112:113], v[112:113], v[48:49]
	s_waitcnt vmcnt(3)
	v_pk_add_f32 v[114:115], v[114:115], v[50:51]
	v_pk_add_f32 v[116:117], v[116:117], v[52:53]
	s_waitcnt vmcnt(2)
	v_pk_add_f32 v[118:119], v[118:119], v[54:55]
	v_pk_add_f32 v[120:121], v[120:121], v[56:57]
	s_waitcnt vmcnt(1)
	v_pk_add_f32 v[122:123], v[122:123], v[58:59]
	v_pk_add_f32 v[124:125], v[124:125], v[60:61]
	s_waitcnt vmcnt(0)
	v_pk_add_f32 v[126:127], v[126:127], v[62:63]
	v_pk_add_f32 v[128:129], v[128:129], v[64:65]
	s_nop 1
	s_add_i32 s53, s30, 0x40000
	v_add_u32_e32 v131, s53, v130
	global_load_dwordx4 v[2:5], v131, s[12:13] sc0 sc1
	v_add_u32_e32 v131, 0x2000, v131
	global_load_dwordx4 v[6:9], v131, s[12:13] sc0 sc1
	v_add_u32_e32 v131, 0x2000, v131
	global_load_dwordx4 v[10:13], v131, s[12:13] sc0 sc1
	v_add_u32_e32 v131, 0x2000, v131
	global_load_dwordx4 v[14:17], v131, s[12:13] sc0 sc1
	v_add_u32_e32 v131, 0x2000, v131
	global_load_dwordx4 v[18:21], v131, s[12:13] sc0 sc1
	v_add_u32_e32 v131, 0x2000, v131
	global_load_dwordx4 v[22:25], v131, s[12:13] sc0 sc1
	v_add_u32_e32 v131, 0x2000, v131
	global_load_dwordx4 v[26:29], v131, s[12:13] sc0 sc1
	v_add_u32_e32 v131, 0x2000, v131
	global_load_dwordx4 v[30:33], v131, s[12:13] sc0 sc1
	v_add_u32_e32 v131, 0x2000, v131
	global_load_dwordx4 v[34:37], v131, s[12:13] sc0 sc1
	v_add_u32_e32 v131, 0x2000, v131
	global_load_dwordx4 v[38:41], v131, s[12:13] sc0 sc1
	v_add_u32_e32 v131, 0x2000, v131
	global_load_dwordx4 v[42:45], v131, s[12:13] sc0 sc1
	v_add_u32_e32 v131, 0x2000, v131
	global_load_dwordx4 v[46:49], v131, s[12:13] sc0 sc1
	v_add_u32_e32 v131, 0x2000, v131
	global_load_dwordx4 v[50:53], v131, s[12:13] sc0 sc1
	v_add_u32_e32 v131, 0x2000, v131
	global_load_dwordx4 v[54:57], v131, s[12:13] sc0 sc1
	v_add_u32_e32 v131, 0x2000, v131
	global_load_dwordx4 v[58:61], v131, s[12:13] sc0 sc1
	v_add_u32_e32 v131, 0x2000, v131
	global_load_dwordx4 v[62:65], v131, s[12:13] sc0 sc1
	v_add_u32_e32 v131, 0x2000, v131
	s_waitcnt vmcnt(15)
	v_pk_add_f32 v[66:67], v[66:67], v[2:3]
	v_pk_add_f32 v[68:69], v[68:69], v[4:5]
	s_waitcnt vmcnt(14)
	v_pk_add_f32 v[70:71], v[70:71], v[6:7]
	v_pk_add_f32 v[72:73], v[72:73], v[8:9]
	s_waitcnt vmcnt(13)
	v_pk_add_f32 v[74:75], v[74:75], v[10:11]
	v_pk_add_f32 v[76:77], v[76:77], v[12:13]
	s_waitcnt vmcnt(12)
	v_pk_add_f32 v[78:79], v[78:79], v[14:15]
	v_pk_add_f32 v[80:81], v[80:81], v[16:17]
	s_waitcnt vmcnt(11)
	v_pk_add_f32 v[82:83], v[82:83], v[18:19]
	v_pk_add_f32 v[84:85], v[84:85], v[20:21]
	s_waitcnt vmcnt(10)
	v_pk_add_f32 v[86:87], v[86:87], v[22:23]
	v_pk_add_f32 v[88:89], v[88:89], v[24:25]
	s_waitcnt vmcnt(9)
	v_pk_add_f32 v[90:91], v[90:91], v[26:27]
	v_pk_add_f32 v[92:93], v[92:93], v[28:29]
	s_waitcnt vmcnt(8)
	v_pk_add_f32 v[94:95], v[94:95], v[30:31]
	v_pk_add_f32 v[96:97], v[96:97], v[32:33]
	s_waitcnt vmcnt(7)
	v_pk_add_f32 v[98:99], v[98:99], v[34:35]
	v_pk_add_f32 v[100:101], v[100:101], v[36:37]
	s_waitcnt vmcnt(6)
	v_pk_add_f32 v[102:103], v[102:103], v[38:39]
	v_pk_add_f32 v[104:105], v[104:105], v[40:41]
	s_waitcnt vmcnt(5)
	v_pk_add_f32 v[106:107], v[106:107], v[42:43]
	v_pk_add_f32 v[108:109], v[108:109], v[44:45]
	s_waitcnt vmcnt(4)
	v_pk_add_f32 v[110:111], v[110:111], v[46:47]
	v_pk_add_f32 v[112:113], v[112:113], v[48:49]
	s_waitcnt vmcnt(3)
	v_pk_add_f32 v[114:115], v[114:115], v[50:51]
	v_pk_add_f32 v[116:117], v[116:117], v[52:53]
	s_waitcnt vmcnt(2)
	v_pk_add_f32 v[118:119], v[118:119], v[54:55]
	v_pk_add_f32 v[120:121], v[120:121], v[56:57]
	s_waitcnt vmcnt(1)
	v_pk_add_f32 v[122:123], v[122:123], v[58:59]
	v_pk_add_f32 v[124:125], v[124:125], v[60:61]
	s_waitcnt vmcnt(0)
	v_pk_add_f32 v[126:127], v[126:127], v[62:63]
	v_pk_add_f32 v[128:129], v[128:129], v[64:65]
	s_nop 1
	s_branch .Lk4_done
; #define PG8_BAR __builtin_amdgcn_s_barrier()
; template <class Epi, bool GS = false>
; __device__ __forceinline__ void gemm_phase(LAS unsigned char* lds, const Gemm g, const StaticOrder& S, const Epi& E, const int tid) {
;     ...
;         if (wr == 0) PG8_BAR;
;         E(acc, cur, wr, wc, fr, fq);
.Lk4_r1:
	s_add_i32 s53, s31, 0x0
	v_add_u32_e32 v131, s53, v130
	global_load_dwordx4 v[66:69], v131, s[12:13] sc0 sc1
	v_add_u32_e32 v131, 0x2000, v131
	global_load_dwordx4 v[70:73], v131, s[12:13] sc0 sc1
	v_add_u32_e32 v131, 0x2000, v131
	global_load_dwordx4 v[74:77], v131, s[12:13] sc0 sc1
	v_add_u32_e32 v131, 0x2000, v131
	global_load_dwordx4 v[78:81], v131, s[12:13] sc0 sc1
	v_add_u32_e32 v131, 0x2000, v131
	global_load_dwordx4 v[82:85], v131, s[12:13] sc0 sc1
	v_add_u32_e32 v131, 0x2000, v131
	global_load_dwordx4 v[86:89], v131, s[12:13] sc0 sc1
	v_add_u32_e32 v131, 0x2000, v131
	global_load_dwordx4 v[90:93], v131, s[12:13] sc0 sc1
	v_add_u32_e32 v131, 0x2000, v131
	global_load_dwordx4 v[94:97], v131, s[12:13] sc0 sc1
	v_add_u32_e32 v131, 0x2000, v131
	global_load_dwordx4 v[98:101], v131, s[12:13] sc0 sc1
	v_add_u32_e32 v131, 0x2000, v131
	global_load_dwordx4 v[102:105], v131, s[12:13] sc0 sc1
	v_add_u32_e32 v131, 0x2000, v131
	global_load_dwordx4 v[106:109], v131, s[12:13] sc0 sc1
	v_add_u32_e32 v131, 0x2000, v131
	global_load_dwordx4 v[110:113], v131, s[12:13] sc0 sc1
	v_add_u32_e32 v131, 0x2000, v131
	global_load_dwordx4 v[114:117], v131, s[12:13] sc0 sc1
	v_add_u32_e32 v131, 0x2000, v131
	global_load_dwordx4 v[118:121], v131, s[12:13] sc0 sc1
	v_add_u32_e32 v131, 0x2000, v131
	global_load_dwordx4 v[122:125], v131, s[12:13] sc0 sc1
	v_add_u32_e32 v131, 0x2000, v131
	global_load_dwordx4 v[126:129], v131, s[12:13] sc0 sc1
	v_add_u32_e32 v131, 0x2000, v131
	s_waitcnt vmcnt(15)
	v_pk_add_f32 v[2:3], v[2:3], v[66:67]
	v_pk_add_f32 v[4:5], v[4:5], v[68:69]
	s_waitcnt vmcnt(14)
	v_pk_add_f32 v[6:7], v[6:7], v[70:71]
	v_pk_add_f32 v[8:9], v[8:9], v[72:73]
	s_waitcnt vmcnt(13)
	v_pk_add_f32 v[10:11], v[10:11], v[74:75]
	v_pk_add_f32 v[12:13], v[12:13], v[76:77]
	s_waitcnt vmcnt(12)
	v_pk_add_f32 v[14:15], v[14:15], v[78:79]
	v_pk_add_f32 v[16:17], v[16:17], v[80:81]
	s_waitcnt vmcnt(11)
	v_pk_add_f32 v[18:19], v[18:19], v[82:83]
	v_pk_add_f32 v[20:21], v[20:21], v[84:85]
	s_waitcnt vmcnt(10)
	v_pk_add_f32 v[22:23], v[22:23], v[86:87]
	v_pk_add_f32 v[24:25], v[24:25], v[88:89]
	s_waitcnt vmcnt(9)
	v_pk_add_f32 v[26:27], v[26:27], v[90:91]
	v_pk_add_f32 v[28:29], v[28:29], v[92:93]
	s_waitcnt vmcnt(8)
	v_pk_add_f32 v[30:31], v[30:31], v[94:95]
	v_pk_add_f32 v[32:33], v[32:33], v[96:97]
	s_waitcnt vmcnt(7)
	v_pk_add_f32 v[34:35], v[34:35], v[98:99]
	v_pk_add_f32 v[36:37], v[36:37], v[100:101]
	s_waitcnt vmcnt(6)
	v_pk_add_f32 v[38:39], v[38:39], v[102:103]
	v_pk_add_f32 v[40:41], v[40:41], v[104:105]
	s_waitcnt vmcnt(5)
	v_pk_add_f32 v[42:43], v[42:43], v[106:107]
	v_pk_add_f32 v[44:45], v[44:45], v[108:109]
	s_waitcnt vmcnt(4)
	v_pk_add_f32 v[46:47], v[46:47], v[110:111]
	v_pk_add_f32 v[48:49], v[48:49], v[112:113]
	s_waitcnt vmcnt(3)
	v_pk_add_f32 v[50:51], v[50:51], v[114:115]
	v_pk_add_f32 v[52:53], v[52:53], v[116:117]
	s_waitcnt vmcnt(2)
	v_pk_add_f32 v[54:55], v[54:55], v[118:119]
	v_pk_add_f32 v[56:57], v[56:57], v[120:121]
	s_waitcnt vmcnt(1)
	v_pk_add_f32 v[58:59], v[58:59], v[122:123]
	v_pk_add_f32 v[60:61], v[60:61], v[124:125]
	s_waitcnt vmcnt(0)
	v_pk_add_f32 v[62:63], v[62:63], v[126:127]
	v_pk_add_f32 v[64:65], v[64:65], v[128:129]
	s_nop 1
	s_add_i32 s53, s31, 0x20000
	v_add_u32_e32 v131, s53, v130
	global_load_dwordx4 v[66:69], v131, s[12:13] sc0 sc1
	v_add_u32_e32 v131, 0x2000, v131
	global_load_dwordx4 v[70:73], v131, s[12:13] sc0 sc1
	v_add_u32_e32 v131, 0x2000, v131
	global_load_dwordx4 v[74:77], v131, s[12:13] sc0 sc1
	v_add_u32_e32 v131, 0x2000, v131
	global_load_dwordx4 v[78:81], v131, s[12:13] sc0 sc1
	v_add_u32_e32 v131, 0x2000, v131
	global_load_dwordx4 v[82:85], v131, s[12:13] sc0 sc1
	v_add_u32_e32 v131, 0x2000, v131
	global_load_dwordx4 v[86:89], v131, s[12:13] sc0 sc1
	v_add_u32_e32 v131, 0x2000, v131
	global_load_dwordx4 v[90:93], v131, s[12:13] sc0 sc1
	v_add_u32_e32 v131, 0x2000, v131
	global_load_dwordx4 v[94:97], v131, s[12:13] sc0 sc1
	v_add_u32_e32 v131, 0x2000, v131
	global_load_dwordx4 v[98:101], v131, s[12:13] sc0 sc1
	v_add_u32_e32 v131, 0x2000, v131
	global_load_dwordx4 v[102:105], v131, s[12:13] sc0 sc1
	v_add_u32_e32 v131, 0x2000, v131
	global_load_dwordx4 v[106:109], v131, s[12:13] sc0 sc1
	v_add_u32_e32 v131, 0x2000, v131
	global_load_dwordx4 v[110:113], v131, s[12:13] sc0 sc1
	v_add_u32_e32 v131, 0x2000, v131
	global_load_dwordx4 v[114:117], v131, s[12:13] sc0 sc1
	v_add_u32_e32 v131, 0x2000, v131
	global_load_dwordx4 v[118:121], v131, s[12:13] sc0 sc1
	v_add_u32_e32 v131, 0x2000, v131
	global_load_dwordx4 v[122:125], v131, s[12:13] sc0 sc1
	v_add_u32_e32 v131, 0x2000, v131
	global_load_dwordx4 v[126:129], v131, s[12:13] sc0 sc1
	v_add_u32_e32 v131, 0x2000, v131
	s_waitcnt vmcnt(15)
	v_pk_add_f32 v[2:3], v[2:3], v[66:67]
	v_pk_add_f32 v[4:5], v[4:5], v[68:69]
	s_waitcnt vmcnt(14)
	v_pk_add_f32 v[6:7], v[6:7], v[70:71]
	v_pk_add_f32 v[8:9], v[8:9], v[72:73]
	s_waitcnt vmcnt(13)
	v_pk_add_f32 v[10:11], v[10:11], v[74:75]
	v_pk_add_f32 v[12:13], v[12:13], v[76:77]
	s_waitcnt vmcnt(12)
	v_pk_add_f32 v[14:15], v[14:15], v[78:79]
	v_pk_add_f32 v[16:17], v[16:17], v[80:81]
	s_waitcnt vmcnt(11)
	v_pk_add_f32 v[18:19], v[18:19], v[82:83]
	v_pk_add_f32 v[20:21], v[20:21], v[84:85]
	s_waitcnt vmcnt(10)
	v_pk_add_f32 v[22:23], v[22:23], v[86:87]
	v_pk_add_f32 v[24:25], v[24:25], v[88:89]
	s_waitcnt vmcnt(9)
	v_pk_add_f32 v[26:27], v[26:27], v[90:91]
	v_pk_add_f32 v[28:29], v[28:29], v[92:93]
	s_waitcnt vmcnt(8)
	v_pk_add_f32 v[30:31], v[30:31], v[94:95]
	v_pk_add_f32 v[32:33], v[32:33], v[96:97]
	s_waitcnt vmcnt(7)
	v_pk_add_f32 v[34:35], v[34:35], v[98:99]
	v_pk_add_f32 v[36:37], v[36:37], v[100:101]
	s_waitcnt vmcnt(6)
; #define PG8_BAR __builtin_amdgcn_s_barrier()
; template <class Epi, bool GS = false>
; __device__ __forceinline__ void gemm_phase(LAS unsigned char* lds, const Gemm g, const StaticOrder& S, const Epi& E, const int tid) {
;     ...
;         if (wr == 0) PG8_BAR;
;         E(acc, cur, wr, wc, fr, fq);
;     __device__ __forceinline__ void operator()(const f32x4 (&acc)[2][2][4][2], const Unit& u, int wr, int wc, int fr, int fq) const {
;         const int col0 = u.pn * BM + wc * 32 + 4 * fq;
; #pragma unroll
;         for (int ai = 0; ai < 2; ++ai) {
;             const int grb = row_base + u.pm * BM + ai * HALF + wr * 64;
;             const int seq = grb < MP ? (grb >> 11) : NPB + ((grb - MP) >> 6);
;             const float* gp = gate + (size_t)seq * (6 * DM) + col0;
;             f32x4 gv[2][2];
; #pragma unroll
;             for (int bj = 0; bj < 2; ++bj)
; #pragma unroll
;                 for (int n = 0; n < 2; ++n) gv[bj][n] = *(const f32x4*)(gp + bj * HALF + n * 16);
;             if (u.part == 0) {
; #pragma unroll
;                 for (int mp = 0; mp < 2; ++mp) {
;                 f32x4 xv[2][2][2];
; #pragma unroll
;                 for (int mm = 0; mm < 2; ++mm) { const int gr = grb + (2 * mp + mm) * 16 + fr;
;                     const float* xr = (gr < MP ? xin_p + (size_t)gr * DM : xin_s + (size_t)(gr - MP) * DM) + col0;
; #pragma unroll
;                     for (int bj = 0; bj < 2; ++bj)
; #pragma unroll
;                         for (int n = 0; n < 2; ++n) xv[mm][bj][n] = *(const f32x4*)(xr + bj * HALF + n * 16); }
; #pragma unroll
;                 for (int mm = 0; mm < 2; ++mm) { const int m = 2 * mp + mm; const int gr = grb + m * 16 + fr; float* orow = out + (size_t)gr * DM + col0;
; #pragma unroll
;                     for (int bj = 0; bj < 2; ++bj)
; #pragma unroll
;                         for (int n = 0; n < 2; ++n) *(f32x4*)(orow + bj * HALF + n * 16) = xv[mm][bj][n] + gv[bj][n] * acc[ai][bj][m][n]; }
	v_pk_add_f32 v[38:39], v[38:39], v[102:103]
	v_pk_add_f32 v[40:41], v[40:41], v[104:105]
	s_waitcnt vmcnt(5)
	v_pk_add_f32 v[42:43], v[42:43], v[106:107]
	v_pk_add_f32 v[44:45], v[44:45], v[108:109]
	s_waitcnt vmcnt(4)
	v_pk_add_f32 v[46:47], v[46:47], v[110:111]
	v_pk_add_f32 v[48:49], v[48:49], v[112:113]
	s_waitcnt vmcnt(3)
	v_pk_add_f32 v[50:51], v[50:51], v[114:115]
	v_pk_add_f32 v[52:53], v[52:53], v[116:117]
	s_waitcnt vmcnt(2)
	v_pk_add_f32 v[54:55], v[54:55], v[118:119]
	v_pk_add_f32 v[56:57], v[56:57], v[120:121]
	s_waitcnt vmcnt(1)
	v_pk_add_f32 v[58:59], v[58:59], v[122:123]
	v_pk_add_f32 v[60:61], v[60:61], v[124:125]
	s_waitcnt vmcnt(0)
	v_pk_add_f32 v[62:63], v[62:63], v[126:127]
	v_pk_add_f32 v[64:65], v[64:65], v[128:129]
	s_nop 1
	s_add_i32 s53, s31, 0x40000
	v_add_u32_e32 v131, s53, v130
	global_load_dwordx4 v[66:69], v131, s[12:13] sc0 sc1
	v_add_u32_e32 v131, 0x2000, v131
	global_load_dwordx4 v[70:73], v131, s[12:13] sc0 sc1
	v_add_u32_e32 v131, 0x2000, v131
	global_load_dwordx4 v[74:77], v131, s[12:13] sc0 sc1
	v_add_u32_e32 v131, 0x2000, v131
	global_load_dwordx4 v[78:81], v131, s[12:13] sc0 sc1
	v_add_u32_e32 v131, 0x2000, v131
	global_load_dwordx4 v[82:85], v131, s[12:13] sc0 sc1
	v_add_u32_e32 v131, 0x2000, v131
	global_load_dwordx4 v[86:89], v131, s[12:13] sc0 sc1
	v_add_u32_e32 v131, 0x2000, v131
	global_load_dwordx4 v[90:93], v131, s[12:13] sc0 sc1
	v_add_u32_e32 v131, 0x2000, v131
	global_load_dwordx4 v[94:97], v131, s[12:13] sc0 sc1
	v_add_u32_e32 v131, 0x2000, v131
	global_load_dwordx4 v[98:101], v131, s[12:13] sc0 sc1
	v_add_u32_e32 v131, 0x2000, v131
	global_load_dwordx4 v[102:105], v131, s[12:13] sc0 sc1
	v_add_u32_e32 v131, 0x2000, v131
	global_load_dwordx4 v[106:109], v131, s[12:13] sc0 sc1
	v_add_u32_e32 v131, 0x2000, v131
	global_load_dwordx4 v[110:113], v131, s[12:13] sc0 sc1
	v_add_u32_e32 v131, 0x2000, v131
	global_load_dwordx4 v[114:117], v131, s[12:13] sc0 sc1
	v_add_u32_e32 v131, 0x2000, v131
	global_load_dwordx4 v[118:121], v131, s[12:13] sc0 sc1
	v_add_u32_e32 v131, 0x2000, v131
	global_load_dwordx4 v[122:125], v131, s[12:13] sc0 sc1
	v_add_u32_e32 v131, 0x2000, v131
	global_load_dwordx4 v[126:129], v131, s[12:13] sc0 sc1
	v_add_u32_e32 v131, 0x2000, v131
	s_waitcnt vmcnt(15)
	v_pk_add_f32 v[2:3], v[2:3], v[66:67]
	v_pk_add_f32 v[4:5], v[4:5], v[68:69]
	s_waitcnt vmcnt(14)
	v_pk_add_f32 v[6:7], v[6:7], v[70:71]
	v_pk_add_f32 v[8:9], v[8:9], v[72:73]
	s_waitcnt vmcnt(13)
	v_pk_add_f32 v[10:11], v[10:11], v[74:75]
	v_pk_add_f32 v[12:13], v[12:13], v[76:77]
	s_waitcnt vmcnt(12)
	v_pk_add_f32 v[14:15], v[14:15], v[78:79]
	v_pk_add_f32 v[16:17], v[16:17], v[80:81]
	s_waitcnt vmcnt(11)
	v_pk_add_f32 v[18:19], v[18:19], v[82:83]
	v_pk_add_f32 v[20:21], v[20:21], v[84:85]
	s_waitcnt vmcnt(10)
	v_pk_add_f32 v[22:23], v[22:23], v[86:87]
	v_pk_add_f32 v[24:25], v[24:25], v[88:89]
	s_waitcnt vmcnt(9)
	v_pk_add_f32 v[26:27], v[26:27], v[90:91]
	v_pk_add_f32 v[28:29], v[28:29], v[92:93]
	s_waitcnt vmcnt(8)
	v_pk_add_f32 v[30:31], v[30:31], v[94:95]
	v_pk_add_f32 v[32:33], v[32:33], v[96:97]
	s_waitcnt vmcnt(7)
	v_pk_add_f32 v[34:35], v[34:35], v[98:99]
	v_pk_add_f32 v[36:37], v[36:37], v[100:101]
	s_waitcnt vmcnt(6)
	v_pk_add_f32 v[38:39], v[38:39], v[102:103]
	v_pk_add_f32 v[40:41], v[40:41], v[104:105]
	s_waitcnt vmcnt(5)
	v_pk_add_f32 v[42:43], v[42:43], v[106:107]
	v_pk_add_f32 v[44:45], v[44:45], v[108:109]
	s_waitcnt vmcnt(4)
	v_pk_add_f32 v[46:47], v[46:47], v[110:111]
	v_pk_add_f32 v[48:49], v[48:49], v[112:113]
	s_waitcnt vmcnt(3)
	v_pk_add_f32 v[50:51], v[50:51], v[114:115]
	v_pk_add_f32 v[52:53], v[52:53], v[116:117]
	s_waitcnt vmcnt(2)
	v_pk_add_f32 v[54:55], v[54:55], v[118:119]
	v_pk_add_f32 v[56:57], v[56:57], v[120:121]
	s_waitcnt vmcnt(1)
	v_pk_add_f32 v[58:59], v[58:59], v[122:123]
	v_pk_add_f32 v[60:61], v[60:61], v[124:125]
	s_waitcnt vmcnt(0)
	v_pk_add_f32 v[62:63], v[62:63], v[126:127]
	v_pk_add_f32 v[64:65], v[64:65], v[128:129]
	s_nop 1
.Lk4_done:
	s_lshl_b32 s22, s48, 8
	s_add_i32 s22, s22, s42
	s_add_i32 s21, s22, 0xffff8000
	s_lshr_b32 s21, s21, 6
	s_ashr_i32 s20, s22, 11
	s_add_i32 s21, s21, 16
	s_cmp_lt_i32 s22, 0x8000
	s_cselect_b32 s20, s20, s21
	v_lshl_or_b32 v130, s49, 8, v191
	s_mul_hi_i32 s21, s20, 0x6000
	s_mulk_i32 s20, 0x6000
	v_ashrrev_i32_e32 v131, 31, v130
	s_add_u32 s20, s40, s20
	s_addc_u32 s21, s41, s21
	v_lshlrev_b64 v[180:181], 2, v[130:131]
	v_lshl_add_u64 v[130:131], s[20:21], 0, v[180:181]
	v_or_b32_e32 v182, s22, v169
	s_mov_b32 s20, 0x8000
	v_readlane_b32 s34, v255, 0
	v_add_u32_e32 v0, 0xffff8000, v182
	v_cmp_gt_i32_e32 vcc, s20, v182
	v_readlane_b32 s35, v255, 1
	v_ashrrev_i32_e32 v183, 31, v182
	v_cndmask_b32_e32 v146, v0, v182, vcc
	v_mov_b32_e32 v0, s35
	v_mov_b32_e32 v148, s25
	v_cndmask_b32_e32 v147, 0, v183, vcc
	v_cndmask_b32_e32 v149, v0, v148, vcc
	v_mov_b32_e32 v0, s34
	v_mov_b32_e32 v148, s24
	v_cndmask_b32_e32 v148, v0, v148, vcc
	v_lshlrev_b64 v[146:147], 12, v[146:147]
	v_lshl_add_u64 v[146:147], v[148:149], 0, v[146:147]
	v_lshl_add_u64 v[146:147], v[146:147], 0, v[180:181]
	global_load_dwordx4 v[142:145], v[130:131], off
	global_load_dwordx4 v[138:141], v[130:131], off offset:64
	global_load_dwordx4 v[134:137], v[130:131], off offset:512
	s_nop 0
	global_load_dwordx4 v[130:133], v[130:131], off offset:576
	s_nop 0
	global_load_dwordx4 v[158:161], v[146:147], off
	global_load_dwordx4 v[154:157], v[146:147], off offset:64
	global_load_dwordx4 v[150:153], v[146:147], off offset:512
	s_nop 0
	global_load_dwordx4 v[146:149], v[146:147], off offset:576
	v_or_b32_e32 v186, 16, v182
	s_movk_i32 s20, 0x7fff
	v_cmp_lt_i32_e32 vcc, s20, v186
	s_and_saveexec_b64 s[20:21], vcc
	s_xor_b64 s[20:21], exec, s[20:21]
	v_add_u32_e32 v0, 0xffff8010, v182
	v_lshlrev_b64 v[184:185], 12, v[0:1]
	v_mov_b32_e32 v187, v1
	v_lshl_add_u64 v[188:189], s[34:35], 0, v[184:185]
	v_lshlrev_b64 v[184:185], 12, v[186:187]
	s_andn2_saveexec_b64 s[20:21], s[20:21]
	v_ashrrev_i32_e32 v187, 31, v186
	v_lshlrev_b64 v[184:185], 12, v[186:187]
	v_lshl_add_u64 v[188:189], s[24:25], 0, v[184:185]
	s_or_b64 exec, exec, s[20:21]
	v_lshl_add_u64 v[194:195], v[188:189], 0, v[180:181]
	global_load_dwordx4 v[186:189], v[194:195], off
	global_load_dwordx4 v[216:219], v[194:195], off offset:64
	global_load_dwordx4 v[220:223], v[194:195], off offset:512
	global_load_dwordx4 v[224:227], v[194:195], off offset:576
	v_lshlrev_b64 v[194:195], 12, v[182:183]
	s_waitcnt vmcnt(0)
;     __device__ __forceinline__ void operator()(const f32x4 (&acc)[2][2][4][2], const Unit& u, int wr, int wc, int fr, int fq) const {
;     ...
;                 for (int mm = 0; mm < 2; ++mm) { const int m = 2 * mp + mm; const int gr = grb + m * 16 + fr; float* orow = out + (size_t)gr * DM + col0;
; #pragma unroll
;                     for (int bj = 0; bj < 2; ++bj)
; #pragma unroll
;                         for (int n = 0; n < 2; ++n) *(f32x4*)(orow + bj * HALF + n * 16) = xv[mm][bj][n] + gv[bj][n] * acc[ai][bj][m][n]; }
	v_pk_fma_f32 v[146:147], v[114:115], v[130:131], v[146:147]
	v_or_b32_e32 v114, 32, v182
	s_mov_b32 s20, 0x8000
	v_pk_fma_f32 v[118:119], v[118:119], v[134:135], v[150:151]
	v_add_u32_e32 v0, 0xffff8020, v182
	v_lshl_add_u64 v[150:151], s[24:25], 0, v[194:195]
	v_ashrrev_i32_e32 v115, 31, v114
	v_cmp_gt_i32_e32 vcc, s20, v114
	v_pk_fma_f32 v[128:129], v[128:129], v[144:145], v[160:161]
	v_pk_fma_f32 v[126:127], v[126:127], v[142:143], v[158:159]
	v_pk_fma_f32 v[124:125], v[124:125], v[140:141], v[156:157]
	v_pk_fma_f32 v[122:123], v[122:123], v[138:139], v[154:155]
	v_pk_fma_f32 v[120:121], v[120:121], v[136:137], v[152:153]
	v_mov_b32_e32 v154, s35
	v_mov_b32_e32 v155, s25
	v_mov_b32_e32 v156, s34
	v_mov_b32_e32 v157, s24
	v_lshl_add_u64 v[150:151], v[150:151], 0, v[180:181]
	v_cndmask_b32_e32 v153, 0, v115, vcc
	v_cndmask_b32_e32 v152, v0, v114, vcc
	v_pk_fma_f32 v[148:149], v[116:117], v[132:133], v[148:149]
	v_lshl_add_u64 v[116:117], s[24:25], 0, v[184:185]
	v_cndmask_b32_e32 v155, v154, v155, vcc
	v_cndmask_b32_e32 v154, v156, v157, vcc
	s_bitcmp1_b32 s100, 1
	s_cselect_b64 exec, 0, -1
	global_store_dwordx4 v[150:151], v[126:129], off
	global_store_dwordx4 v[150:151], v[122:125], off offset:64
	global_store_dwordx4 v[150:151], v[118:121], off offset:512
	global_store_dwordx4 v[150:151], v[146:149], off offset:576
	s_mov_b64 exec, -1
	v_lshl_add_u64 v[116:117], v[116:117], 0, v[180:181]
	v_lshlrev_b64 v[118:119], 12, v[152:153]
	v_lshl_add_u64 v[118:119], v[154:155], 0, v[118:119]
	v_lshl_add_u64 v[118:119], v[118:119], 0, v[180:181]
	s_movk_i32 s20, 0x7fff
	v_pk_fma_f32 v[112:113], v[112:113], v[144:145], v[188:189]
	v_pk_fma_f32 v[110:111], v[110:111], v[142:143], v[186:187]
	v_pk_fma_f32 v[108:109], v[108:109], v[140:141], v[218:219]
	v_pk_fma_f32 v[106:107], v[106:107], v[138:139], v[216:217]
	v_pk_fma_f32 v[104:105], v[104:105], v[136:137], v[222:223]
	v_pk_fma_f32 v[102:103], v[102:103], v[134:135], v[220:221]
	v_pk_fma_f32 v[100:101], v[100:101], v[132:133], v[226:227]
	v_pk_fma_f32 v[98:99], v[98:99], v[130:131], v[224:225]
	s_bitcmp1_b32 s100, 1
	s_cselect_b64 exec, 0, -1
	global_store_dwordx4 v[116:117], v[110:113], off
	global_store_dwordx4 v[116:117], v[106:109], off offset:64
	global_store_dwordx4 v[116:117], v[102:105], off offset:512
	global_store_dwordx4 v[116:117], v[98:101], off offset:576
	s_mov_b64 exec, -1
	global_load_dwordx4 v[110:113], v[118:119], off
	s_nop 0
	global_load_dwordx4 v[106:109], v[118:119], off offset:64
	global_load_dwordx4 v[102:105], v[118:119], off offset:512
	global_load_dwordx4 v[98:101], v[118:119], off offset:576
	v_or_b32_e32 v118, 48, v182
	v_cmp_lt_i32_e32 vcc, s20, v118
	s_and_saveexec_b64 s[20:21], vcc
	s_xor_b64 s[20:21], exec, s[20:21]
	v_add_u32_e32 v0, 0xffff8030, v182
	v_lshlrev_b64 v[116:117], 12, v[0:1]
	v_mov_b32_e32 v119, v1
	v_lshl_add_u64 v[120:121], s[34:35], 0, v[116:117]
	v_lshlrev_b64 v[116:117], 12, v[118:119]
	s_andn2_saveexec_b64 s[20:21], s[20:21]
	v_ashrrev_i32_e32 v119, 31, v118
	v_lshlrev_b64 v[116:117], 12, v[118:119]
	v_lshl_add_u64 v[120:121], s[24:25], 0, v[116:117]
	s_or_b64 exec, exec, s[20:21]
	v_lshl_add_u64 v[146:147], v[120:121], 0, v[180:181]
	global_load_dwordx4 v[118:121], v[146:147], off
	global_load_dwordx4 v[122:125], v[146:147], off offset:64
	global_load_dwordx4 v[126:129], v[146:147], off offset:512
	s_nop 0
	global_load_dwordx4 v[146:149], v[146:147], off offset:576
	s_add_i32 s20, s22, 0x80
	s_addk_i32 s22, 0x8080
	s_lshr_b32 s22, s22, 6
	v_lshlrev_b64 v[114:115], 12, v[114:115]
	s_waitcnt vmcnt(4)
	v_pk_fma_f32 v[82:83], v[82:83], v[130:131], v[98:99]
	v_lshl_add_u64 v[98:99], s[24:25], 0, v[116:117]
	s_ashr_i32 s21, s20, 11
	s_add_i32 s22, s22, 16
	v_pk_fma_f32 v[86:87], v[86:87], v[134:135], v[102:103]
	v_pk_fma_f32 v[84:85], v[84:85], v[132:133], v[100:101]
	v_lshl_add_u64 v[100:101], s[24:25], 0, v[114:115]
	v_lshl_add_u64 v[102:103], v[98:99], 0, v[180:181]
	v_or_b32_e32 v98, s20, v169
	s_cmp_lt_i32 s20, 0x8000
	s_mov_b32 s20, 0x8000
	v_pk_fma_f32 v[96:97], v[96:97], v[144:145], v[112:113]
	v_pk_fma_f32 v[94:95], v[94:95], v[142:143], v[110:111]
	v_pk_fma_f32 v[90:91], v[90:91], v[138:139], v[106:107]
	v_lshl_add_u64 v[100:101], v[100:101], 0, v[180:181]
	v_ashrrev_i32_e32 v99, 31, v98
	v_add_u32_e32 v107, 0xffff8000, v98
	v_cmp_gt_i32_e32 vcc, s20, v98
	s_cselect_b32 s20, s21, s22
	v_pk_fma_f32 v[92:93], v[92:93], v[140:141], v[108:109]
	v_pk_fma_f32 v[88:89], v[88:89], v[136:137], v[104:105]
	v_mov_b32_e32 v0, s35
	v_mov_b32_e32 v104, s25
	v_mov_b32_e32 v105, s34
	v_mov_b32_e32 v106, s24
	s_bitcmp1_b32 s100, 1
	s_cselect_b64 exec, 0, -1
	global_store_dwordx4 v[100:101], v[94:97], off
	global_store_dwordx4 v[100:101], v[90:93], off offset:64
	global_store_dwordx4 v[100:101], v[86:89], off offset:512
	global_store_dwordx4 v[100:101], v[82:85], off offset:576
	s_mov_b64 exec, -1
	s_mul_hi_i32 s21, s20, 0x6000
	s_mulk_i32 s20, 0x6000
	v_cndmask_b32_e32 v83, 0, v99, vcc
	v_cndmask_b32_e32 v82, v107, v98, vcc
	v_cndmask_b32_e32 v85, v0, v104, vcc
	v_cndmask_b32_e32 v84, v105, v106, vcc
	v_lshlrev_b64 v[82:83], 12, v[82:83]
	s_add_u32 s20, s40, s20
	v_lshl_add_u64 v[82:83], v[84:85], 0, v[82:83]
	s_addc_u32 s21, s41, s21
	v_lshl_add_u64 v[82:83], v[82:83], 0, v[180:181]
	v_lshl_add_u64 v[84:85], s[20:21], 0, v[180:181]
	s_movk_i32 s20, 0x7fff
	s_waitcnt vmcnt(7)
	v_pk_fma_f32 v[80:81], v[80:81], v[144:145], v[120:121]
	v_pk_fma_f32 v[78:79], v[78:79], v[142:143], v[118:119]
	s_waitcnt vmcnt(6)
	v_pk_fma_f32 v[76:77], v[76:77], v[140:141], v[124:125]
	v_pk_fma_f32 v[74:75], v[74:75], v[138:139], v[122:123]
	s_waitcnt vmcnt(5)
;     __device__ __forceinline__ void operator()(const f32x4 (&acc)[2][2][4][2], const Unit& u, int wr, int wc, int fr, int fq) const {
;     ...
;                 for (int mm = 0; mm < 2; ++mm) { const int m = 2 * mp + mm; const int gr = grb + m * 16 + fr; float* orow = out + (size_t)gr * DM + col0;
; #pragma unroll
;                     for (int bj = 0; bj < 2; ++bj)
; #pragma unroll
;                         for (int n = 0; n < 2; ++n) *(f32x4*)(orow + bj * HALF + n * 16) = xv[mm][bj][n] + gv[bj][n] * acc[ai][bj][m][n]; }
	v_pk_fma_f32 v[72:73], v[72:73], v[136:137], v[128:129]
	v_pk_fma_f32 v[70:71], v[70:71], v[134:135], v[126:127]
	s_waitcnt vmcnt(4)
	v_pk_fma_f32 v[68:69], v[68:69], v[132:133], v[148:149]
	v_pk_fma_f32 v[66:67], v[66:67], v[130:131], v[146:147]
	s_bitcmp1_b32 s100, 1
	s_cselect_b64 exec, 0, -1
	global_store_dwordx4 v[102:103], v[78:81], off
	global_store_dwordx4 v[102:103], v[74:77], off offset:64
	global_store_dwordx4 v[102:103], v[70:73], off offset:512
	global_store_dwordx4 v[102:103], v[66:69], off offset:576
	s_mov_b64 exec, -1
	global_load_dwordx4 v[78:81], v[84:85], off
	s_nop 0
	global_load_dwordx4 v[74:77], v[84:85], off offset:64
	global_load_dwordx4 v[70:73], v[84:85], off offset:512
	global_load_dwordx4 v[66:69], v[84:85], off offset:576
	global_load_dwordx4 v[94:97], v[82:83], off
	global_load_dwordx4 v[90:93], v[82:83], off offset:64
	global_load_dwordx4 v[86:89], v[82:83], off offset:512
	s_nop 0
	global_load_dwordx4 v[82:85], v[82:83], off offset:576
	v_or_b32_e32 v102, 16, v98
	v_cmp_lt_i32_e32 vcc, s20, v102
	s_and_saveexec_b64 s[20:21], vcc
	s_xor_b64 s[20:21], exec, s[20:21]
	v_add_u32_e32 v0, 0xffff8010, v98
	v_lshlrev_b64 v[100:101], 12, v[0:1]
	v_mov_b32_e32 v103, v1
	v_lshl_add_u64 v[104:105], s[34:35], 0, v[100:101]
	v_lshlrev_b64 v[100:101], 12, v[102:103]
	s_andn2_saveexec_b64 s[20:21], s[20:21]
	v_ashrrev_i32_e32 v103, 31, v102
	v_lshlrev_b64 v[100:101], 12, v[102:103]
	v_lshl_add_u64 v[104:105], s[24:25], 0, v[100:101]
	s_or_b64 exec, exec, s[20:21]
	v_lshl_add_u64 v[114:115], v[104:105], 0, v[180:181]
	global_load_dwordx4 v[102:105], v[114:115], off
	global_load_dwordx4 v[106:109], v[114:115], off offset:64
	global_load_dwordx4 v[110:113], v[114:115], off offset:512
	s_nop 0
	global_load_dwordx4 v[114:117], v[114:115], off offset:576
	v_lshlrev_b64 v[118:119], 12, v[98:99]
	s_waitcnt vmcnt(4)
	v_pk_fma_f32 v[82:83], v[50:51], v[66:67], v[82:83]
	v_or_b32_e32 v50, 32, v98
	s_mov_b32 s20, 0x8000
	v_pk_fma_f32 v[54:55], v[54:55], v[70:71], v[86:87]
	v_add_u32_e32 v0, 0xffff8020, v98
	v_lshl_add_u64 v[86:87], s[24:25], 0, v[118:119]
	v_ashrrev_i32_e32 v51, 31, v50
	v_cmp_gt_i32_e32 vcc, s20, v50
	v_pk_fma_f32 v[64:65], v[64:65], v[80:81], v[96:97]
	v_pk_fma_f32 v[62:63], v[62:63], v[78:79], v[94:95]
	v_pk_fma_f32 v[60:61], v[60:61], v[76:77], v[92:93]
	v_pk_fma_f32 v[58:59], v[58:59], v[74:75], v[90:91]
	v_pk_fma_f32 v[56:57], v[56:57], v[72:73], v[88:89]
	v_mov_b32_e32 v90, s35
	v_mov_b32_e32 v91, s25
	v_mov_b32_e32 v92, s34
	v_mov_b32_e32 v93, s24
	v_lshl_add_u64 v[86:87], v[86:87], 0, v[180:181]
	v_cndmask_b32_e32 v89, 0, v51, vcc
	v_cndmask_b32_e32 v88, v0, v50, vcc
	v_pk_fma_f32 v[84:85], v[52:53], v[68:69], v[84:85]
	v_lshl_add_u64 v[52:53], s[24:25], 0, v[100:101]
	v_cndmask_b32_e32 v91, v90, v91, vcc
	v_cndmask_b32_e32 v90, v92, v93, vcc
	s_bitcmp1_b32 s100, 0
	s_cselect_b64 exec, 0, -1
	global_store_dwordx4 v[86:87], v[62:65], off
	global_store_dwordx4 v[86:87], v[58:61], off offset:64
	global_store_dwordx4 v[86:87], v[54:57], off offset:512
	global_store_dwordx4 v[86:87], v[82:85], off offset:576
	s_mov_b64 exec, -1
	v_lshl_add_u64 v[52:53], v[52:53], 0, v[180:181]
	v_lshlrev_b64 v[54:55], 12, v[88:89]
	v_lshl_add_u64 v[54:55], v[90:91], 0, v[54:55]
	v_lshl_add_u64 v[54:55], v[54:55], 0, v[180:181]
	s_movk_i32 s20, 0x7fff
	s_waitcnt vmcnt(7)
	v_pk_fma_f32 v[48:49], v[48:49], v[80:81], v[104:105]
	v_pk_fma_f32 v[46:47], v[46:47], v[78:79], v[102:103]
	s_waitcnt vmcnt(6)
	v_pk_fma_f32 v[44:45], v[44:45], v[76:77], v[108:109]
	v_pk_fma_f32 v[42:43], v[42:43], v[74:75], v[106:107]
	s_waitcnt vmcnt(5)
	v_pk_fma_f32 v[40:41], v[40:41], v[72:73], v[112:113]
	v_pk_fma_f32 v[38:39], v[38:39], v[70:71], v[110:111]
	s_waitcnt vmcnt(4)
	v_pk_fma_f32 v[36:37], v[36:37], v[68:69], v[116:117]
	v_pk_fma_f32 v[34:35], v[34:35], v[66:67], v[114:115]
	s_bitcmp1_b32 s100, 0
	s_cselect_b64 exec, 0, -1
	global_store_dwordx4 v[52:53], v[46:49], off
	global_store_dwordx4 v[52:53], v[42:45], off offset:64
	global_store_dwordx4 v[52:53], v[38:41], off offset:512
	global_store_dwordx4 v[52:53], v[34:37], off offset:576
	s_mov_b64 exec, -1
	global_load_dwordx4 v[46:49], v[54:55], off
	s_nop 0
	global_load_dwordx4 v[42:45], v[54:55], off offset:64
	global_load_dwordx4 v[38:41], v[54:55], off offset:512
	global_load_dwordx4 v[34:37], v[54:55], off offset:576
	v_or_b32_e32 v54, 48, v98
	v_cmp_lt_i32_e32 vcc, s20, v54
	s_and_saveexec_b64 s[20:21], vcc
	s_xor_b64 s[20:21], exec, s[20:21]
	v_add_u32_e32 v0, 0xffff8030, v98
	v_lshlrev_b64 v[52:53], 12, v[0:1]
	v_mov_b32_e32 v55, v1
	v_lshl_add_u64 v[56:57], s[34:35], 0, v[52:53]
	v_lshlrev_b64 v[52:53], 12, v[54:55]
	s_andn2_saveexec_b64 s[20:21], s[20:21]
	v_ashrrev_i32_e32 v55, 31, v54
	v_lshlrev_b64 v[52:53], 12, v[54:55]
	v_lshl_add_u64 v[56:57], s[24:25], 0, v[52:53]
	s_or_b64 exec, exec, s[20:21]
	v_lshl_add_u64 v[82:83], v[56:57], 0, v[180:181]
	global_load_dwordx4 v[54:57], v[82:83], off
	global_load_dwordx4 v[58:61], v[82:83], off offset:64
	global_load_dwordx4 v[62:65], v[82:83], off offset:512
	s_nop 0
	global_load_dwordx4 v[82:85], v[82:83], off offset:576
	v_lshlrev_b64 v[50:51], 12, v[50:51]
	s_waitcnt vmcnt(4)
	v_pk_fma_f32 v[20:21], v[20:21], v[68:69], v[36:37]
	v_pk_fma_f32 v[18:19], v[18:19], v[66:67], v[34:35]
	v_lshl_add_u64 v[34:35], s[24:25], 0, v[52:53]
	v_lshl_add_u64 v[36:37], s[24:25], 0, v[50:51]
	v_pk_fma_f32 v[32:33], v[32:33], v[80:81], v[48:49]
	v_pk_fma_f32 v[30:31], v[30:31], v[78:79], v[46:47]
	s_and_b64 vcc, exec, s[4:5]
	v_lshl_add_u64 v[34:35], v[34:35], 0, v[180:181]
	v_lshl_add_u64 v[36:37], v[36:37], 0, v[180:181]
	s_mov_b64 s[4:5], -1
	v_pk_fma_f32 v[28:29], v[28:29], v[76:77], v[44:45]
	v_pk_fma_f32 v[26:27], v[26:27], v[74:75], v[42:43]
	v_pk_fma_f32 v[24:25], v[24:25], v[72:73], v[40:41]
	v_pk_fma_f32 v[22:23], v[22:23], v[70:71], v[38:39]
	s_bitcmp1_b32 s100, 0
	s_cselect_b64 exec, 0, -1
	global_store_dwordx4 v[36:37], v[30:33], off
	global_store_dwordx4 v[36:37], v[26:29], off offset:64
	global_store_dwordx4 v[36:37], v[22:25], off offset:512
	global_store_dwordx4 v[36:37], v[18:21], off offset:576
	s_mov_b64 exec, -1
	s_waitcnt vmcnt(7)
	v_pk_fma_f32 v[16:17], v[16:17], v[80:81], v[56:57]
	v_pk_fma_f32 v[14:15], v[14:15], v[78:79], v[54:55]
	s_waitcnt vmcnt(6)
	v_pk_fma_f32 v[12:13], v[12:13], v[76:77], v[60:61]
	v_pk_fma_f32 v[10:11], v[10:11], v[74:75], v[58:59]
	s_waitcnt vmcnt(5)
	v_pk_fma_f32 v[8:9], v[8:9], v[72:73], v[64:65]
	v_pk_fma_f32 v[6:7], v[6:7], v[70:71], v[62:63]
	s_waitcnt vmcnt(4)
	v_pk_fma_f32 v[4:5], v[4:5], v[68:69], v[84:85]
	v_pk_fma_f32 v[2:3], v[2:3], v[66:67], v[82:83]
	s_bitcmp1_b32 s100, 0
	s_cselect_b64 exec, 0, -1
	global_store_dwordx4 v[34:35], v[14:17], off
	global_store_dwordx4 v[34:35], v[10:13], off offset:64
	global_store_dwordx4 v[34:35], v[6:9], off offset:512
	global_store_dwordx4 v[34:35], v[2:5], off offset:576
	s_mov_b64 exec, -1
	s_cbranch_vccnz .LBB0_985
	s_andn2_b64 vcc, exec, s[8:9]
	s_cbranch_vccnz .LBB0_984
	s_barrier
	s_branch .LBB0_984
